# mout dir-1 epilogue: CAT stores widened to dwordx4 via v_permlane16_swap pairs (8 stores instead of 16 dwordx2)
# baseline (speedup 1.0000x reference)
; #define LAS __attribute__((address_space(3)))
; __device__ __forceinline__ void mout_phase(const Params& p, LAS unsigned char* lds) {
;     ...
;         { const float aj = fv[256 + j];
; #pragma unroll
;           for (int nb = 0; nb < 17; ++nb) acc[nb] = acc[nb] * aj; }
;         __syncthreads();
; #pragma unroll
;         for (int i = 0; i < 8; ++i) { const int idx = t + 512 * i; *(LAS u32x4*)(T + (idx >> 4) * 136 + (idx & 15) * 8) = vreg[i]; }
;         if (t < 256) { const int r = 256 + (t >> 4), c8 = (t & 15) * 8; const unsigned one = (r == 256) ? 0x3F803F80u : 0u; *(LAS u32x4*)(T + r * 136 + c8) = (u32x4){one, one, one, one}; }
;         const float einv = fv[384 + j];
;         { const int un = (u & 1) ? u - 1 + 2 * (int)gridDim.x : u + 1; if (un < 2048) mout_issue(p, un, kreg, qf, gg); }
;         __syncthreads();
; #pragma unroll
;         for (int kk = 0; kk < 4; ++kk) { const bf16x8 sf = *(const LAS bf16x8*)(sb + j * 136 + kk * 32 + fq * 8);
; #pragma unroll
;             for (int nb = 0; nb < 17; ++nb) { const bf16x8 vf = *(const LAS bf16x8*)(T + (nb * 16 + fr) * 136 + kk * 32 + fq * 8);
;                 acc[nb] = __builtin_amdgcn_mfma_f32_16x16x32_bf16(vf, sf, acc[nb], 0, 0, 0); } }
.LBB0_1510:
	v_pk_mul_f32 v[102:103], v[62:63], v[138:139] op_sel_hi:[1,0]
	v_pk_mul_f32 v[100:101], v[60:61], v[138:139] op_sel_hi:[1,0]
	v_pk_mul_f32 v[98:99], v[66:67], v[138:139] op_sel_hi:[1,0]
	v_pk_mul_f32 v[96:97], v[64:65], v[138:139] op_sel_hi:[1,0]
	v_pk_mul_f32 v[66:67], v[74:75], v[138:139] op_sel_hi:[1,0]
	v_pk_mul_f32 v[64:65], v[72:73], v[138:139] op_sel_hi:[1,0]
	v_pk_mul_f32 v[62:63], v[78:79], v[138:139] op_sel_hi:[1,0]
	v_pk_mul_f32 v[60:61], v[76:77], v[138:139] op_sel_hi:[1,0]
	s_waitcnt lgkmcnt(0)
	s_barrier
	ds_read_b128 v[76:79], v200
	ds_read_b128 v[72:75], v201
	v_pk_mul_f32 v[126:127], v[38:39], v[138:139] op_sel_hi:[1,0]
	v_pk_mul_f32 v[124:125], v[36:37], v[138:139] op_sel_hi:[1,0]
	v_pk_mul_f32 v[114:115], v[50:51], v[138:139] op_sel_hi:[1,0]
	v_pk_mul_f32 v[112:113], v[48:49], v[138:139] op_sel_hi:[1,0]
	v_pk_mul_f32 v[50:51], v[90:91], v[138:139] op_sel_hi:[1,0]
	v_pk_mul_f32 v[48:49], v[88:89], v[138:139] op_sel_hi:[1,0]
	s_waitcnt lgkmcnt(0)
	v_mfma_f32_16x16x32_bf16 v[88:91], v[72:75], v[76:79], v[124:127]
	ds_read_b128 v[72:75], v201 offset:4352
	v_pk_mul_f32 v[122:123], v[42:43], v[138:139] op_sel_hi:[1,0]
	v_pk_mul_f32 v[120:121], v[40:41], v[138:139] op_sel_hi:[1,0]
	v_pk_mul_f32 v[118:119], v[46:47], v[138:139] op_sel_hi:[1,0]
	v_pk_mul_f32 v[116:117], v[44:45], v[138:139] op_sel_hi:[1,0]
	s_waitcnt lgkmcnt(0)
	v_mfma_f32_16x16x32_bf16 v[120:123], v[72:75], v[76:79], v[120:123]
	ds_read_b128 v[72:75], v201 offset:8704
	v_pk_mul_f32 v[110:111], v[54:55], v[138:139] op_sel_hi:[1,0]
	v_pk_mul_f32 v[108:109], v[52:53], v[138:139] op_sel_hi:[1,0]
	s_waitcnt lgkmcnt(0)
	v_mfma_f32_16x16x32_bf16 v[116:119], v[72:75], v[76:79], v[116:119]
	ds_read_b128 v[72:75], v201 offset:13056
	v_pk_mul_f32 v[106:107], v[58:59], v[138:139] op_sel_hi:[1,0]
	v_pk_mul_f32 v[104:105], v[56:57], v[138:139] op_sel_hi:[1,0]
	s_waitcnt lgkmcnt(0)
	v_mfma_f32_16x16x32_bf16 v[112:115], v[72:75], v[76:79], v[112:115]
	ds_read_b128 v[72:75], v201 offset:17408
	v_pk_mul_f32 v[46:47], v[94:95], v[138:139] op_sel_hi:[1,0]
	v_pk_mul_f32 v[44:45], v[92:93], v[138:139] op_sel_hi:[1,0]
	s_waitcnt lgkmcnt(0)
	v_mfma_f32_16x16x32_bf16 v[108:111], v[72:75], v[76:79], v[108:111]
	ds_read_b128 v[72:75], v201 offset:21760
	v_pk_mul_f32 v[58:59], v[82:83], v[138:139] op_sel_hi:[1,0]
	v_pk_mul_f32 v[56:57], v[80:81], v[138:139] op_sel_hi:[1,0]
	s_waitcnt lgkmcnt(0)
	v_mfma_f32_16x16x32_bf16 v[104:107], v[72:75], v[76:79], v[104:107]
	ds_read_b128 v[72:75], v201 offset:26112
	v_pk_mul_f32 v[70:71], v[70:71], v[138:139] op_sel_hi:[1,0]
	v_pk_mul_f32 v[68:69], v[68:69], v[138:139] op_sel_hi:[1,0]
	s_waitcnt lgkmcnt(0)
	v_mfma_f32_16x16x32_bf16 v[92:95], v[72:75], v[76:79], v[100:103]
	ds_read_b128 v[72:75], v201 offset:30464
	v_pk_mul_f32 v[54:55], v[86:87], v[138:139] op_sel_hi:[1,0]
	v_pk_mul_f32 v[52:53], v[84:85], v[138:139] op_sel_hi:[1,0]
	s_waitcnt lgkmcnt(0)
	v_mfma_f32_16x16x32_bf16 v[80:83], v[72:75], v[76:79], v[96:99]
	ds_read_b128 v[72:75], v201 offset:34816
	v_pk_mul_f32 v[42:43], v[130:131], v[138:139] op_sel_hi:[1,0]
	v_pk_mul_f32 v[40:41], v[128:129], v[138:139] op_sel_hi:[1,0]
	s_waitcnt lgkmcnt(0)
	v_mfma_f32_16x16x32_bf16 v[72:75], v[72:75], v[76:79], v[68:71]
	s_nop 2
	ds_read_b128 v[68:71], v201 offset:39168
	v_pk_mul_f32 v[38:39], v[134:135], v[138:139] op_sel_hi:[1,0]
	v_pk_mul_f32 v[36:37], v[132:133], v[138:139] op_sel_hi:[1,0]
	s_waitcnt lgkmcnt(0)
	v_mfma_f32_16x16x32_bf16 v[64:67], v[68:71], v[76:79], v[64:67]
	ds_read_b128 v[68:71], v201 offset:43520
	s_lshl_b32 s70, s84, 9
	v_lshlrev_b32_e32 v138, 1, v136
	s_waitcnt lgkmcnt(0)
	v_mfma_f32_16x16x32_bf16 v[60:63], v[68:71], v[76:79], v[60:63]
	ds_read_b128 v[228:231], v201 offset:47872
	ds_read_b128 v[232:235], v201 offset:52224
	ds_read_b128 v[236:239], v201 offset:56576
	ds_read_b128 v[240:243], v201 offset:60928
	ds_read_b128 v[246:249], v201 offset:65280
	s_waitcnt lgkmcnt(4)
	v_mfma_f32_16x16x32_bf16 v[56:59], v[228:231], v[76:79], v[56:59]
	ds_read_b128 v[68:71], v212
	s_waitcnt lgkmcnt(4)
	v_mfma_f32_16x16x32_bf16 v[52:55], v[232:235], v[76:79], v[52:55]
	s_waitcnt lgkmcnt(3)
	v_mfma_f32_16x16x32_bf16 v[48:51], v[236:239], v[76:79], v[48:51]
	s_waitcnt lgkmcnt(2)
	v_mfma_f32_16x16x32_bf16 v[44:47], v[240:243], v[76:79], v[44:47]
	s_waitcnt lgkmcnt(1)
	v_mfma_f32_16x16x32_bf16 v[40:43], v[246:249], v[76:79], v[40:43]
	s_waitcnt lgkmcnt(0)
	v_mfma_f32_16x16x32_bf16 v[36:39], v[68:71], v[76:79], v[36:39]
	ds_read_b128 v[84:87], v200 offset:64
	ds_read_b128 v[68:71], v201 offset:64
	ds_read_b128 v[100:103], v201 offset:17472
	ds_read_b128 v[76:79], v201 offset:4416
	s_waitcnt lgkmcnt(1)
	v_mfma_f32_16x16x32_bf16 v[100:103], v[100:103], v[84:87], v[108:111]
	s_nop 2
	ds_read_b128 v[108:111], v201 offset:21824
	ds_read_b128 v[96:99], v201 offset:13120
	s_waitcnt lgkmcnt(1)
	v_mfma_f32_16x16x32_bf16 v[104:107], v[108:111], v[84:87], v[104:107]
	ds_read_b128 v[108:111], v201 offset:26176
	s_waitcnt lgkmcnt(0)
	v_mfma_f32_16x16x32_bf16 v[92:95], v[108:111], v[84:87], v[92:95]
	ds_read_b128 v[108:111], v201 offset:30528
	s_waitcnt lgkmcnt(0)
	v_mfma_f32_16x16x32_bf16 v[80:83], v[108:111], v[84:87], v[80:83]
	ds_read_b128 v[108:111], v201 offset:34880
	v_mfma_f32_16x16x32_bf16 v[68:71], v[68:71], v[84:87], v[88:91]
	s_nop 2
	ds_read_b128 v[88:91], v201 offset:8768
	s_waitcnt lgkmcnt(1)
	v_mfma_f32_16x16x32_bf16 v[72:75], v[108:111], v[84:87], v[72:75]
	ds_read_b128 v[228:231], v201 offset:39232
	ds_read_b128 v[232:235], v201 offset:43584
	ds_read_b128 v[236:239], v201 offset:47936
	ds_read_b128 v[240:243], v201 offset:52288
	ds_read_b128 v[246:249], v201 offset:56640
	ds_read_b128 v[250:253], v201 offset:60992
	s_waitcnt lgkmcnt(5)
; #define LAS __attribute__((address_space(3)))
; __device__ __forceinline__ void mout_phase(const Params& p, LAS unsigned char* lds) {
;     ...
;         for (int kk = 0; kk < 4; ++kk) { const bf16x8 sf = *(const LAS bf16x8*)(sb + j * 136 + kk * 32 + fq * 8);
; #pragma unroll
;             for (int nb = 0; nb < 17; ++nb) { const bf16x8 vf = *(const LAS bf16x8*)(T + (nb * 16 + fr) * 136 + kk * 32 + fq * 8);
;                 acc[nb] = __builtin_amdgcn_mfma_f32_16x16x32_bf16(vf, sf, acc[nb], 0, 0, 0); } }
;         const float nq = __shfl(acc[16][0], fr);
;         const float inv = 1.f / fmaxf(fabsf(nq), einv);
;         bf16_t* hd = (bf16_t*)(p.ws + WS_HDIR) + (size_t)(r0 + j) * 1024 + h * 256;
	v_mfma_f32_16x16x32_bf16 v[64:67], v[228:231], v[84:87], v[64:67]
	ds_read_b128 v[108:111], v201 offset:65344
	s_waitcnt lgkmcnt(5)
	v_mfma_f32_16x16x32_bf16 v[60:63], v[232:235], v[84:87], v[60:63]
	s_waitcnt lgkmcnt(4)
	v_mfma_f32_16x16x32_bf16 v[56:59], v[236:239], v[84:87], v[56:59]
	s_waitcnt lgkmcnt(3)
	v_mfma_f32_16x16x32_bf16 v[52:55], v[240:243], v[84:87], v[52:55]
	s_waitcnt lgkmcnt(2)
	v_mfma_f32_16x16x32_bf16 v[48:51], v[246:249], v[84:87], v[48:51]
	s_waitcnt lgkmcnt(1)
	v_mfma_f32_16x16x32_bf16 v[44:47], v[250:253], v[84:87], v[44:47]
	s_waitcnt lgkmcnt(0)
	v_mfma_f32_16x16x32_bf16 v[40:43], v[108:111], v[84:87], v[40:43]
	ds_read_b128 v[108:111], v212 offset:64
	v_mfma_f32_16x16x32_bf16 v[76:79], v[76:79], v[84:87], v[120:123]
	v_mfma_f32_16x16x32_bf16 v[88:91], v[88:91], v[84:87], v[116:119]
	v_mfma_f32_16x16x32_bf16 v[96:99], v[96:99], v[84:87], v[112:115]
	s_waitcnt lgkmcnt(0)
	v_mfma_f32_16x16x32_bf16 v[36:39], v[108:111], v[84:87], v[36:39]
	ds_read_b128 v[84:87], v200 offset:128
	ds_read_b128 v[108:111], v201 offset:128
	s_waitcnt lgkmcnt(0)
	v_mfma_f32_16x16x32_bf16 v[108:111], v[108:111], v[84:87], v[68:71]
	s_nop 2
	ds_read_b128 v[228:231], v201 offset:4480
	ds_read_b128 v[232:235], v201 offset:8832
	ds_read_b128 v[236:239], v201 offset:13184
	ds_read_b128 v[240:243], v201 offset:17536
	ds_read_b128 v[246:249], v201 offset:21888
	ds_read_b128 v[250:253], v201 offset:26240
	s_waitcnt lgkmcnt(5)
	v_mfma_f32_16x16x32_bf16 v[76:79], v[228:231], v[84:87], v[76:79]
	ds_read_b128 v[228:231], v201 offset:30592
	s_waitcnt lgkmcnt(5)
	v_mfma_f32_16x16x32_bf16 v[88:91], v[232:235], v[84:87], v[88:91]
	ds_read_b128 v[232:235], v201 offset:34944
	s_waitcnt lgkmcnt(5)
	v_mfma_f32_16x16x32_bf16 v[96:99], v[236:239], v[84:87], v[96:99]
	ds_read_b128 v[68:71], v201 offset:39296
	s_waitcnt lgkmcnt(5)
	v_mfma_f32_16x16x32_bf16 v[112:115], v[240:243], v[84:87], v[100:103]
	s_waitcnt lgkmcnt(4)
	v_mfma_f32_16x16x32_bf16 v[104:107], v[246:249], v[84:87], v[104:107]
	s_waitcnt lgkmcnt(3)
	v_mfma_f32_16x16x32_bf16 v[116:119], v[250:253], v[84:87], v[92:95]
	s_waitcnt lgkmcnt(2)
	v_mfma_f32_16x16x32_bf16 v[80:83], v[228:231], v[84:87], v[80:83]
	s_waitcnt lgkmcnt(1)
	v_mfma_f32_16x16x32_bf16 v[72:75], v[232:235], v[84:87], v[72:75]
	s_waitcnt lgkmcnt(0)
	v_mfma_f32_16x16x32_bf16 v[120:123], v[68:71], v[84:87], v[64:67]
	s_nop 2
	ds_read_b128 v[64:67], v201 offset:43648
	s_waitcnt lgkmcnt(0)
	v_mfma_f32_16x16x32_bf16 v[68:71], v[64:67], v[84:87], v[60:63]
	s_nop 2
	ds_read_b128 v[60:63], v201 offset:48000
	s_waitcnt lgkmcnt(0)
	v_mfma_f32_16x16x32_bf16 v[64:67], v[60:63], v[84:87], v[56:59]
	s_nop 2
	ds_read_b128 v[56:59], v201 offset:52352
	s_waitcnt lgkmcnt(0)
	v_mfma_f32_16x16x32_bf16 v[60:63], v[56:59], v[84:87], v[52:55]
	s_nop 2
	ds_read_b128 v[52:55], v201 offset:56704
	s_waitcnt lgkmcnt(0)
	v_mfma_f32_16x16x32_bf16 v[52:55], v[52:55], v[84:87], v[48:51]
	s_nop 2
	ds_read_b128 v[48:51], v201 offset:61056
	s_waitcnt lgkmcnt(0)
	v_mfma_f32_16x16x32_bf16 v[48:51], v[48:51], v[84:87], v[44:47]
	s_nop 2
	ds_read_b128 v[44:47], v201 offset:65408
	s_waitcnt lgkmcnt(0)
	v_mfma_f32_16x16x32_bf16 v[44:47], v[44:47], v[84:87], v[40:43]
	s_nop 2
	ds_read_b128 v[40:43], v212 offset:128
	s_waitcnt lgkmcnt(0)
	v_mfma_f32_16x16x32_bf16 v[100:103], v[40:43], v[84:87], v[36:39]
	ds_read_b128 v[124:127], v200 offset:192
	s_nop 1
	ds_read_b128 v[36:39], v201 offset:192
	ds_read_b128 v[40:43], v201 offset:4544
	ds_read_b128 v[56:59], v201 offset:8896
	s_waitcnt lgkmcnt(1)
	v_mfma_f32_16x16x32_bf16 v[40:43], v[40:43], v[124:127], v[76:79]
	s_nop 2
	ds_read_b128 v[76:79], v201 offset:13248
	ds_read_b128 v[84:87], v201 offset:17600
	s_waitcnt lgkmcnt(1)
	v_mfma_f32_16x16x32_bf16 v[76:79], v[76:79], v[124:127], v[96:99]
	s_waitcnt lgkmcnt(0)
	v_mfma_f32_16x16x32_bf16 v[96:99], v[84:87], v[124:127], v[112:115]
	ds_read_b128 v[84:87], v201 offset:21952
	s_waitcnt lgkmcnt(0)
	v_mfma_f32_16x16x32_bf16 v[92:95], v[84:87], v[124:127], v[104:107]
	ds_read_b128 v[84:87], v201 offset:26304
	s_nop 1
	ds_read_b128 v[104:107], v201 offset:43712
	v_mfma_f32_16x16x32_bf16 v[56:59], v[56:59], v[124:127], v[88:91]
	s_waitcnt lgkmcnt(1)
	v_mfma_f32_16x16x32_bf16 v[88:91], v[84:87], v[124:127], v[116:119]
	ds_read_b128 v[84:87], v201 offset:30656
	s_waitcnt lgkmcnt(0)
	v_mfma_f32_16x16x32_bf16 v[84:87], v[84:87], v[124:127], v[80:83]
	s_nop 2
	ds_read_b128 v[80:83], v201 offset:35008
	s_waitcnt lgkmcnt(0)
	v_mfma_f32_16x16x32_bf16 v[80:83], v[80:83], v[124:127], v[72:75]
	s_nop 2
	ds_read_b128 v[72:75], v201 offset:39360
	v_mfma_f32_16x16x32_bf16 v[68:71], v[104:107], v[124:127], v[68:71]
	ds_read_b128 v[228:231], v201 offset:48064
	ds_read_b128 v[232:235], v201 offset:52416
	ds_read_b128 v[236:239], v201 offset:56768
	ds_read_b128 v[240:243], v201 offset:61120
	ds_read_b128 v[246:249], v201 offset:65472
	s_waitcnt lgkmcnt(4)
	v_mfma_f32_16x16x32_bf16 v[64:67], v[228:231], v[124:127], v[64:67]
	ds_read_b128 v[104:107], v212 offset:192
	s_waitcnt lgkmcnt(4)
	v_mfma_f32_16x16x32_bf16 v[60:63], v[232:235], v[124:127], v[60:63]
	s_waitcnt lgkmcnt(3)
	v_mfma_f32_16x16x32_bf16 v[52:55], v[236:239], v[124:127], v[52:55]
	s_waitcnt lgkmcnt(2)
	v_mfma_f32_16x16x32_bf16 v[48:51], v[240:243], v[124:127], v[48:51]
	s_waitcnt lgkmcnt(1)
	v_mfma_f32_16x16x32_bf16 v[44:47], v[246:249], v[124:127], v[44:47]
	s_waitcnt lgkmcnt(0)
	v_mfma_f32_16x16x32_bf16 v[100:103], v[104:107], v[124:127], v[100:103]
	v_lshl_add_u32 v106, s85, 7, v194
	s_nop 6
	v_and_or_b32 v101, v224, 64, v147
	v_lshlrev_b32_e32 v101, 2, v101
	ds_bpermute_b32 v100, v101, v100
	v_max_f32_e32 v101, v153, v153
	v_ashrrev_i32_e32 v107, 31, v106
	v_mfma_f32_16x16x32_bf16 v[36:39], v[36:39], v[124:127], v[108:111]
	s_waitcnt lgkmcnt(0)
	v_max_f32_e64 v100, |v100|, |v100|
	v_max_f32_e32 v100, v100, v101
	v_div_scale_f32 v101, s[80:81], v100, v100, 1.0
	v_rcp_f32_e32 v102, v101
	v_mfma_f32_16x16x32_bf16 v[72:75], v[72:75], v[124:127], v[120:123]
	s_mov_b64 s[80:81], -1
	v_fma_f32 v103, -v101, v102, 1.0
	v_fmac_f32_e32 v102, v103, v102
	v_div_scale_f32 v103, vcc, 1.0, v100, 1.0
	v_mul_f32_e32 v104, v103, v102
	v_fma_f32 v105, -v101, v104, v103
	v_fmac_f32_e32 v104, v105, v102
	v_fma_f32 v101, -v101, v104, v103
	v_div_fmas_f32 v101, v101, v102, v104
	v_lshlrev_b64 v[102:103], 11, v[106:107]
	v_lshl_add_u64 v[102:103], s[2:3], 0, v[102:103]
	v_lshl_add_u64 v[102:103], v[102:103], 0, s[70:71]
	v_div_fixup_f32 v100, v101, v100, 1.0
	v_lshl_add_u64 v[102:103], v[102:103], 0, v[138:139]
	s_and_b64 vcc, exec, s[66:67]
	s_cbranch_vccnz .LBB0_1512
; __device__ __forceinline__ float bflo(unsigned u) { return __uint_as_float(u << 16); }
; __device__ __forceinline__ float bfhi(unsigned u) { return __uint_as_float(u & 0xffff0000u); }
; __device__ __forceinline__ void mout_phase(const Params& p, LAS unsigned char* lds) {
;     ...
;             float ss = 0.f;
; #pragma unroll
;             for (int nb = 0; nb < 16; ++nb) { const u32x2 hv = *(const u32x2*)(hd + nb * 16 + 4 * fq);
;                 acc[nb][0] = acc[nb][0] * inv + bflo(hv.x); acc[nb][1] = acc[nb][1] * inv + bfhi(hv.x); acc[nb][2] = acc[nb][2] * inv + bflo(hv.y); acc[nb][3] = acc[nb][3] * inv + bfhi(hv.y);
;                 ss += acc[nb][0] * acc[nb][0] + acc[nb][1] * acc[nb][1] + acc[nb][2] * acc[nb][2] + acc[nb][3] * acc[nb][3]; }
;             ss += __shfl_xor(ss, 16); ss += __shfl_xor(ss, 32);
	global_load_dwordx2 v[104:105], v[102:103], off
	global_load_dwordx2 v[110:111], v[102:103], off offset:32
	global_load_dwordx2 v[112:113], v[102:103], off offset:64
	global_load_dwordx2 v[114:115], v[102:103], off offset:96
	global_load_dwordx2 v[116:117], v[102:103], off offset:128
	global_load_dwordx2 v[118:119], v[102:103], off offset:160
	global_load_dwordx2 v[120:121], v[102:103], off offset:192
	global_load_dwordx2 v[122:123], v[102:103], off offset:224
	global_load_dwordx2 v[124:125], v[102:103], off offset:256
	global_load_dwordx2 v[130:131], v[102:103], off offset:288
	global_load_dwordx2 v[132:133], v[102:103], off offset:320
	global_load_dwordx2 v[134:135], v[102:103], off offset:352
	v_mov_b32_e32 v213, v244
	v_readlane_b32 s36, v255, 48
	v_lshlrev_b64 v[108:109], 10, v[106:107]
	v_readlane_b32 s37, v255, 49
	s_lshl_b32 s80, s84, 8
	v_lshlrev_b64 v[106:107], 12, v[106:107]
	v_lshl_add_u64 v[108:109], v[108:109], 1, s[36:37]
	v_readlane_b32 s36, v255, 50
	v_readlane_b32 s37, v255, 51
	s_lshl_b32 s70, s80, 1
	v_lshl_add_u64 v[108:109], v[108:109], 0, s[70:71]
	v_lshl_add_u64 v[106:107], s[36:37], 0, v[106:107]
	v_lshl_add_u64 v[108:109], v[108:109], 0, v[138:139]
	v_xor_b32_e32 v225, 16, v224
	s_waitcnt vmcnt(11)
	v_and_b32_e32 v163, 0xffff0000, v104
	s_waitcnt vmcnt(10)
	v_and_b32_e32 v171, 0xffff0000, v110
	v_lshlrev_b32_e32 v161, 16, v104
	v_lshlrev_b32_e32 v169, 16, v110
	s_waitcnt vmcnt(9)
	v_and_b32_e32 v236, 0xffff0000, v112
	v_fmac_f32_e32 v163, v37, v100
	v_fmac_f32_e32 v171, v41, v100
	v_lshlrev_b32_e32 v165, 16, v105
	v_and_b32_e32 v167, 0xffff0000, v105
	v_lshlrev_b32_e32 v173, 16, v111
	v_lshlrev_b32_e32 v177, 16, v112
	s_waitcnt vmcnt(8)
	v_and_b32_e32 v240, 0xffff0000, v114
	v_fmac_f32_e32 v161, v36, v100
	v_fmac_f32_e32 v169, v40, v100
	v_fmac_f32_e32 v236, v57, v100
	v_mul_f32_e32 v104, v163, v163
	v_mul_f32_e32 v105, v171, v171
	v_and_b32_e32 v175, 0xffff0000, v111
	v_lshlrev_b32_e32 v237, 16, v113
	v_lshlrev_b32_e32 v239, 16, v114
	s_waitcnt vmcnt(7)
	v_and_b32_e32 v244, 0xffff0000, v116
	v_fmac_f32_e32 v165, v38, v100
	v_fmac_f32_e32 v173, v42, v100
	v_fmac_f32_e32 v177, v56, v100
	v_fmac_f32_e32 v240, v77, v100
	v_mul_f32_e32 v110, v236, v236
	v_fmac_f32_e32 v104, v161, v161
	v_fmac_f32_e32 v105, v169, v169
	v_and_b32_e32 v238, 0xffff0000, v113
	v_lshlrev_b32_e32 v241, 16, v115
	v_lshlrev_b32_e32 v243, 16, v116
	s_waitcnt vmcnt(6)
	v_and_b32_e32 v155, 0xffff0000, v118
	v_fmac_f32_e32 v167, v39, v100
	v_fmac_f32_e32 v175, v43, v100
	v_fmac_f32_e32 v237, v58, v100
	v_fmac_f32_e32 v239, v76, v100
	v_fmac_f32_e32 v244, v97, v100
	v_mul_f32_e32 v111, v240, v240
	v_fmac_f32_e32 v110, v177, v177
	v_fmac_f32_e32 v104, v165, v165
	v_fmac_f32_e32 v105, v173, v173
	v_and_b32_e32 v242, 0xffff0000, v115
	v_lshlrev_b32_e32 v245, 16, v117
	v_lshlrev_b32_e32 v159, 16, v118
	v_fmac_f32_e32 v238, v59, v100
	v_fmac_f32_e32 v241, v78, v100
	v_fmac_f32_e32 v243, v96, v100
	v_fmac_f32_e32 v155, v93, v100
	v_mul_f32_e32 v112, v244, v244
	v_fmac_f32_e32 v111, v239, v239
	v_fmac_f32_e32 v110, v237, v237
	v_fmac_f32_e32 v104, v167, v167
	v_fmac_f32_e32 v105, v175, v175
	v_and_b32_e32 v246, 0xffff0000, v117
	v_lshlrev_b32_e32 v153, 16, v119
	v_fmac_f32_e32 v242, v79, v100
	v_fmac_f32_e32 v245, v98, v100
	v_fmac_f32_e32 v159, v92, v100
	v_mul_f32_e32 v113, v155, v155
	v_fmac_f32_e32 v112, v243, v243
	v_fmac_f32_e32 v111, v241, v241
	v_fmac_f32_e32 v110, v238, v238
	v_add_f32_e32 v104, v104, v105
	v_and_b32_e32 v101, 0xffff0000, v119
	v_fmac_f32_e32 v246, v99, v100
	v_fmac_f32_e32 v153, v94, v100
	v_fmac_f32_e32 v113, v159, v159
	v_fmac_f32_e32 v112, v245, v245
	v_fmac_f32_e32 v111, v242, v242
	v_add_f32_e32 v104, v104, v110
	v_fmac_f32_e32 v101, v95, v100
	v_fmac_f32_e32 v113, v153, v153
	v_fmac_f32_e32 v112, v246, v246
	v_add_f32_e32 v104, v104, v111
	v_fmac_f32_e32 v113, v101, v101
	v_add_f32_e32 v104, v104, v112
	v_add_f32_e32 v104, v104, v113
	global_load_dwordx2 v[110:111], v[102:103], off offset:384
	global_load_dwordx2 v[112:113], v[102:103], off offset:416
	global_load_dwordx2 v[116:117], v[102:103], off offset:448
	global_load_dwordx2 v[230:231], v[102:103], off offset:480
	s_waitcnt vmcnt(9)
	v_and_b32_e32 v248, 0xffff0000, v120
	v_lshlrev_b32_e32 v247, 16, v120
	v_fmac_f32_e32 v248, v89, v100
	v_fmac_f32_e32 v247, v88, v100
	v_lshlrev_b32_e32 v249, 16, v121
	v_mul_f32_e32 v105, v248, v248
	v_fmac_f32_e32 v249, v90, v100
	v_and_b32_e32 v250, 0xffff0000, v121
	v_fmac_f32_e32 v105, v247, v247
	v_fmac_f32_e32 v250, v91, v100
	v_fmac_f32_e32 v105, v249, v249
	s_waitcnt vmcnt(8)
	v_and_b32_e32 v252, 0xffff0000, v122
	v_fmac_f32_e32 v105, v250, v250
	v_lshlrev_b32_e32 v251, 16, v122
	v_fmac_f32_e32 v252, v85, v100
	v_add_f32_e32 v104, v104, v105
	v_fmac_f32_e32 v251, v84, v100
	v_lshlrev_b32_e32 v253, 16, v123
	v_mul_f32_e32 v105, v252, v252
	v_fmac_f32_e32 v253, v86, v100
	v_and_b32_e32 v141, 0xffff0000, v123
	v_fmac_f32_e32 v105, v251, v251
	v_fmac_f32_e32 v141, v87, v100
	v_fmac_f32_e32 v105, v253, v253
	v_fmac_f32_e32 v105, v141, v141
	v_add_f32_e32 v118, v104, v105
	v_mov_b32_e32 v104, v80
	v_mov_b32_e32 v105, v72
	s_waitcnt vmcnt(6)
	v_lshlrev_b32_e32 v115, 16, v130
	v_lshlrev_b32_e32 v114, 16, v124
	v_pk_fma_f32 v[126:127], v[104:105], v[100:101], v[114:115] op_sel_hi:[1,0,1]
	v_mov_b32_e32 v104, v81
	v_mov_b32_e32 v105, v73
	v_and_b32_e32 v115, 0xffff0000, v130
	v_and_b32_e32 v114, 0xffff0000, v124
	v_pk_fma_f32 v[128:129], v[104:105], v[100:101], v[114:115] op_sel_hi:[1,0,1]
	v_mov_b32_e32 v104, v82
	v_mov_b32_e32 v105, v74
	v_lshlrev_b32_e32 v115, 16, v131
	v_lshlrev_b32_e32 v114, 16, v125
	v_pk_fma_f32 v[180:181], v[104:105], v[100:101], v[114:115] op_sel_hi:[1,0,1]
	v_mov_b32_e32 v104, v83
	v_mov_b32_e32 v105, v75
	v_and_b32_e32 v115, 0xffff0000, v131
	v_and_b32_e32 v114, 0xffff0000, v125
	v_pk_fma_f32 v[182:183], v[104:105], v[100:101], v[114:115] op_sel_hi:[1,0,1]
	v_pk_mul_f32 v[104:105], v[128:129], v[128:129]
	s_waitcnt vmcnt(4)
; __device__ __forceinline__ float bflo(unsigned u) { return __uint_as_float(u << 16); }
; __device__ __forceinline__ float bfhi(unsigned u) { return __uint_as_float(u & 0xffff0000u); }
; __device__ __forceinline__ void mout_phase(const Params& p, LAS unsigned char* lds) {
;     ...
;             float ss = 0.f;
; #pragma unroll
;             for (int nb = 0; nb < 16; ++nb) { const u32x2 hv = *(const u32x2*)(hd + nb * 16 + 4 * fq);
;                 acc[nb][0] = acc[nb][0] * inv + bflo(hv.x); acc[nb][1] = acc[nb][1] * inv + bfhi(hv.x); acc[nb][2] = acc[nb][2] * inv + bflo(hv.y); acc[nb][3] = acc[nb][3] * inv + bfhi(hv.y);
;                 ss += acc[nb][0] * acc[nb][0] + acc[nb][1] * acc[nb][1] + acc[nb][2] * acc[nb][2] + acc[nb][3] * acc[nb][3]; }
;             ss += __shfl_xor(ss, 16); ss += __shfl_xor(ss, 32);
;             const float rstd = rsqrtf(ss * (1.f / 256.f) + 1e-6f);
;             const float* ng = p.in[15] + h * 256;
;             const bf16_t* og = (const bf16_t*)(p.ws + WS_O) + (size_t)(r0 + j) * 1024 + h * 256;
;             bf16_t* cat = (bf16_t*)(p.ws + WS_CAT) + (size_t)(r0 + j) * 2048 + h * 256;
; #pragma unroll
;             for (int nb = 0; nb < 16; ++nb) { const int dv = nb * 16 + 4 * fq; const f32x4 gn = *(const f32x4*)(ng + dv); const u32x2 ov = *(const u32x2*)(og + dv);
	v_lshlrev_b32_e32 v115, 16, v134
	v_pk_fma_f32 v[104:105], v[126:127], v[126:127], v[104:105]
	v_lshlrev_b32_e32 v114, 16, v132
	v_pk_fma_f32 v[104:105], v[180:181], v[180:181], v[104:105]
	global_load_dwordx2 v[232:233], v[108:109], off
	v_pk_fma_f32 v[104:105], v[182:183], v[182:183], v[104:105]
	s_waitcnt vmcnt(2)
	v_lshlrev_b32_e32 v234, 16, v117
	v_add_f32_e32 v104, v118, v104
	v_add_f32_e32 v130, v104, v105
	v_mov_b32_e32 v104, v68
	v_mov_b32_e32 v105, v64
	v_pk_fma_f32 v[118:119], v[104:105], v[100:101], v[114:115] op_sel_hi:[1,0,1]
	v_mov_b32_e32 v104, v69
	v_mov_b32_e32 v105, v65
	v_and_b32_e32 v115, 0xffff0000, v134
	v_and_b32_e32 v114, 0xffff0000, v132
	v_pk_fma_f32 v[120:121], v[104:105], v[100:101], v[114:115] op_sel_hi:[1,0,1]
	v_mov_b32_e32 v104, v70
	v_mov_b32_e32 v105, v66
	v_lshlrev_b32_e32 v115, 16, v135
	v_lshlrev_b32_e32 v114, 16, v133
	v_pk_fma_f32 v[122:123], v[104:105], v[100:101], v[114:115] op_sel_hi:[1,0,1]
	v_mov_b32_e32 v104, v71
	v_mov_b32_e32 v105, v67
	v_and_b32_e32 v115, 0xffff0000, v135
	v_and_b32_e32 v114, 0xffff0000, v133
	v_pk_fma_f32 v[124:125], v[104:105], v[100:101], v[114:115] op_sel_hi:[1,0,1]
	v_pk_mul_f32 v[104:105], v[120:121], v[120:121]
	v_lshlrev_b32_e32 v115, 16, v112
	v_pk_fma_f32 v[104:105], v[118:119], v[118:119], v[104:105]
	v_lshlrev_b32_e32 v114, 16, v110
	v_pk_fma_f32 v[104:105], v[122:123], v[122:123], v[104:105]
	v_and_b32_e32 v133, 0xffff0000, v112
	v_pk_fma_f32 v[104:105], v[124:125], v[124:125], v[104:105]
	v_and_b32_e32 v132, 0xffff0000, v110
	v_add_f32_e32 v104, v130, v104
	v_lshl_add_u64 v[130:131], v[106:107], 0, s[70:71]
	s_lshl_b32 s70, s80, 2
	v_lshl_add_u64 v[106:107], v[150:151], 0, s[70:71]
	global_load_dwordx4 v[226:229], v[106:107], off
	v_add_f32_e32 v157, v104, v105
	v_mov_b32_e32 v104, v60
	v_mov_b32_e32 v105, v52
	v_pk_fma_f32 v[104:105], v[104:105], v[100:101], v[114:115] op_sel_hi:[1,0,1]
	v_mov_b32_e32 v114, v61
	v_mov_b32_e32 v115, v53
	v_pk_fma_f32 v[132:133], v[114:115], v[100:101], v[132:133] op_sel_hi:[1,0,1]
	v_mov_b32_e32 v114, v62
	v_mov_b32_e32 v115, v54
	v_lshlrev_b32_e32 v135, 16, v113
	v_lshlrev_b32_e32 v134, 16, v111
	v_and_b32_e32 v112, 0xffff0000, v111
	v_pk_mul_f32 v[110:111], v[132:133], v[132:133]
	v_pk_fma_f32 v[134:135], v[114:115], v[100:101], v[134:135] op_sel_hi:[1,0,1]
	v_mov_b32_e32 v114, v63
	v_mov_b32_e32 v115, v55
	v_and_b32_e32 v113, 0xffff0000, v113
	v_pk_fma_f32 v[110:111], v[104:105], v[104:105], v[110:111]
	v_pk_fma_f32 v[178:179], v[114:115], v[100:101], v[112:113] op_sel_hi:[1,0,1]
	v_pk_fma_f32 v[110:111], v[134:135], v[134:135], v[110:111]
	s_waitcnt vmcnt(2)
	v_lshlrev_b32_e32 v113, 16, v230
	v_pk_fma_f32 v[110:111], v[178:179], v[178:179], v[110:111]
	v_lshlrev_b32_e32 v112, 16, v116
	v_add_f32_e32 v110, v157, v110
	v_add_f32_e32 v157, v110, v111
	v_mov_b32_e32 v110, v48
	v_mov_b32_e32 v111, v44
	v_pk_fma_f32 v[110:111], v[110:111], v[100:101], v[112:113] op_sel_hi:[1,0,1]
	v_mov_b32_e32 v112, v49
	v_mov_b32_e32 v113, v45
	v_and_b32_e32 v115, 0xffff0000, v230
	v_and_b32_e32 v114, 0xffff0000, v116
	v_pk_fma_f32 v[112:113], v[112:113], v[100:101], v[114:115] op_sel_hi:[1,0,1]
	v_mov_b32_e32 v114, v50
	v_mov_b32_e32 v115, v46
	v_lshlrev_b32_e32 v235, 16, v231
	v_pk_fma_f32 v[114:115], v[114:115], v[100:101], v[234:235] op_sel_hi:[1,0,1]
	v_mov_b32_e32 v234, v51
	v_mov_b32_e32 v235, v47
	v_and_b32_e32 v231, 0xffff0000, v231
	v_and_b32_e32 v230, 0xffff0000, v117
	v_pk_fma_f32 v[116:117], v[234:235], v[100:101], v[230:231] op_sel_hi:[1,0,1]
	v_pk_mul_f32 v[230:231], v[112:113], v[112:113]
	s_mov_b32 s70, 0x800000
	v_pk_fma_f32 v[230:231], v[110:111], v[110:111], v[230:231]
	v_lshl_add_u64 v[130:131], v[130:131], 0, v[138:139]
	v_pk_fma_f32 v[230:231], v[114:115], v[114:115], v[230:231]
	s_mov_b64 s[80:81], 0
	v_pk_fma_f32 v[230:231], v[116:117], v[116:117], v[230:231]
	s_nop 0
	v_add_f32_e32 v157, v157, v230
	v_and_b32_e32 v230, 64, v224
	v_add_u32_e32 v230, 64, v230
	v_cmp_lt_i32_e32 vcc, v225, v230
	v_add_f32_e32 v157, v157, v231
	s_nop 0
	v_cndmask_b32_e32 v225, v224, v225, vcc
	v_lshlrev_b32_e32 v225, 2, v225
	ds_bpermute_b32 v225, v225, v157
	s_waitcnt lgkmcnt(0)
	v_add_f32_e32 v157, v157, v225
	v_xor_b32_e32 v225, 32, v224
	v_cmp_lt_i32_e32 vcc, v225, v230
	s_nop 1
	v_cndmask_b32_e32 v224, v224, v225, vcc
	v_lshlrev_b32_e32 v224, 2, v224
	ds_bpermute_b32 v224, v224, v157
	s_waitcnt lgkmcnt(0)
	v_add_f32_e32 v157, v157, v224
	v_mov_b32_e32 v224, 0x358637bd
	v_fmamk_f32 v157, v157, 0x3b800000, v224
	v_mul_f32_e32 v224, 0x4b800000, v157
	v_cmp_gt_f32_e32 vcc, s70, v157
	s_nop 1
	v_cndmask_b32_e32 v157, v157, v224, vcc
	v_rsq_f32_e32 v157, v157
	s_nop 0
	v_mul_f32_e32 v224, 0x45800000, v157
	v_cndmask_b32_e32 v157, v157, v224, vcc
	global_load_dwordx2 v[36:37], v[108:109], off offset:32
	global_load_dwordx2 v[38:39], v[108:109], off offset:64
	global_load_dwordx2 v[40:41], v[108:109], off offset:96
	global_load_dwordx2 v[42:43], v[108:109], off offset:128
	global_load_dwordx2 v[44:45], v[108:109], off offset:160
	global_load_dwordx2 v[46:47], v[108:109], off offset:192
	global_load_dwordx2 v[48:49], v[108:109], off offset:224
	global_load_dwordx2 v[50:51], v[108:109], off offset:256
	global_load_dwordx2 v[52:53], v[108:109], off offset:288
	global_load_dwordx2 v[54:55], v[108:109], off offset:320
	global_load_dwordx2 v[56:57], v[108:109], off offset:352
	global_load_dwordx2 v[58:59], v[108:109], off offset:384
	global_load_dwordx2 v[60:61], v[108:109], off offset:416
	global_load_dwordx2 v[62:63], v[108:109], off offset:448
	global_load_dwordx2 v[64:65], v[108:109], off offset:480
	global_load_dwordx4 v[68:71], v[106:107], off offset:64
	global_load_dwordx4 v[72:75], v[106:107], off offset:128
	global_load_dwordx4 v[76:79], v[106:107], off offset:192
	global_load_dwordx4 v[80:83], v[106:107], off offset:256
	global_load_dwordx4 v[84:87], v[106:107], off offset:320
	global_load_dwordx4 v[88:91], v[106:107], off offset:384
	global_load_dwordx4 v[92:95], v[106:107], off offset:448
	global_load_dwordx4 v[96:99], v[106:107], off offset:512
	v_bfe_u32 v230, v140, 4, 1
	v_mul_u32_u24_e32 v230, 24, v230
	v_mov_b32_e32 v231, 0
	v_lshl_add_u64 v[130:131], v[130:131], 0, v[230:231]
	s_waitcnt vmcnt(23)
; __device__ __forceinline__ unsigned cvt_pk_bf16(float lo, float hi) { unsigned r; asm volatile("v_cvt_pk_bf16_f32 %0, %1, %2" : "=v"(r) : "v"(lo), "v"(hi)); return r; }
; __device__ __forceinline__ float bflo(unsigned u) { return __uint_as_float(u << 16); }
; __device__ __forceinline__ float bfhi(unsigned u) { return __uint_as_float(u & 0xffff0000u); }
; __device__ __forceinline__ void mout_phase(const Params& p, LAS unsigned char* lds) {
;     ...
;             for (int nb = 0; nb < 16; ++nb) { const int dv = nb * 16 + 4 * fq; const f32x4 gn = *(const f32x4*)(ng + dv); const u32x2 ov = *(const u32x2*)(og + dv);
;                 u32x2 o; o.x = cvt_pk_bf16(acc[nb][0] * rstd * gn[0] * bflo(ov.x), acc[nb][1] * rstd * gn[1] * bfhi(ov.x));
;                 o.y = cvt_pk_bf16(acc[nb][2] * rstd * gn[2] * bflo(ov.y), acc[nb][3] * rstd * gn[3] * bfhi(ov.y));
;                 *(u32x2*)(cat + dv) = o;
;                 if ((nb & 3) == 3) asm volatile("" ::: "memory"); }
	v_mul_f32_e32 v161, v161, v157
	v_mul_f32_e32 v161, v161, v226
	v_lshlrev_b32_e32 v230, 16, v232
	v_mul_f32_e32 v161, v161, v230
	v_mul_f32_e32 v163, v163, v157
	v_mul_f32_e32 v163, v163, v227
	v_and_b32_e32 v230, 0xffff0000, v232
	v_mul_f32_e32 v163, v163, v230
	v_mul_f32_e32 v165, v165, v157
	v_mul_f32_e32 v165, v165, v228
	v_lshlrev_b32_e32 v230, 16, v233
	v_mul_f32_e32 v165, v165, v230
	v_mul_f32_e32 v167, v167, v157
	v_mul_f32_e32 v167, v167, v229
	v_and_b32_e32 v230, 0xffff0000, v233
	v_mul_f32_e32 v167, v167, v230
	v_cvt_pk_bf16_f32 v224, v161, v163
	v_cvt_pk_bf16_f32 v225, v165, v167
	s_waitcnt vmcnt(7)
	v_mul_f32_e32 v169, v169, v157
	v_mul_f32_e32 v169, v169, v68
	v_lshlrev_b32_e32 v230, 16, v36
	v_mul_f32_e32 v169, v169, v230
	v_mul_f32_e32 v171, v171, v157
	v_mul_f32_e32 v171, v171, v69
	v_and_b32_e32 v230, 0xffff0000, v36
	v_mul_f32_e32 v171, v171, v230
	v_mul_f32_e32 v173, v173, v157
	v_mul_f32_e32 v173, v173, v70
	v_lshlrev_b32_e32 v230, 16, v37
	v_mul_f32_e32 v173, v173, v230
	v_mul_f32_e32 v175, v175, v157
	v_mul_f32_e32 v175, v175, v71
	v_and_b32_e32 v230, 0xffff0000, v37
	v_mul_f32_e32 v175, v175, v230
	v_cvt_pk_bf16_f32 v226, v169, v171
	v_cvt_pk_bf16_f32 v227, v173, v175
	s_nop 1
	v_permlane16_swap_b32_e32 v224, v226
	v_permlane16_swap_b32_e32 v225, v227
	global_store_dwordx4 v[130:131], v[224:227], off
	s_waitcnt vmcnt(7)
	v_mul_f32_e32 v177, v177, v157
	v_mul_f32_e32 v177, v177, v72
	v_lshlrev_b32_e32 v230, 16, v38
	v_mul_f32_e32 v177, v177, v230
	v_mul_f32_e32 v236, v236, v157
	v_mul_f32_e32 v236, v236, v73
	v_and_b32_e32 v230, 0xffff0000, v38
	v_mul_f32_e32 v236, v236, v230
	v_mul_f32_e32 v237, v237, v157
	v_mul_f32_e32 v237, v237, v74
	v_lshlrev_b32_e32 v230, 16, v39
	v_mul_f32_e32 v237, v237, v230
	v_mul_f32_e32 v238, v238, v157
	v_mul_f32_e32 v238, v238, v75
	v_and_b32_e32 v230, 0xffff0000, v39
	v_mul_f32_e32 v238, v238, v230
	v_cvt_pk_bf16_f32 v224, v177, v236
	v_cvt_pk_bf16_f32 v225, v237, v238
	s_waitcnt vmcnt(6)
	v_mul_f32_e32 v239, v239, v157
	v_mul_f32_e32 v239, v239, v76
	v_lshlrev_b32_e32 v230, 16, v40
	v_mul_f32_e32 v239, v239, v230
	v_mul_f32_e32 v240, v240, v157
	v_mul_f32_e32 v240, v240, v77
	v_and_b32_e32 v230, 0xffff0000, v40
	v_mul_f32_e32 v240, v240, v230
	v_mul_f32_e32 v241, v241, v157
	v_mul_f32_e32 v241, v241, v78
	v_lshlrev_b32_e32 v230, 16, v41
	v_mul_f32_e32 v241, v241, v230
	v_mul_f32_e32 v242, v242, v157
	v_mul_f32_e32 v242, v242, v79
	v_and_b32_e32 v230, 0xffff0000, v41
	v_mul_f32_e32 v242, v242, v230
	v_cvt_pk_bf16_f32 v226, v239, v240
	v_cvt_pk_bf16_f32 v227, v241, v242
	s_nop 1
	v_permlane16_swap_b32_e32 v224, v226
	v_permlane16_swap_b32_e32 v225, v227
	global_store_dwordx4 v[130:131], v[224:227], off offset:64
	s_waitcnt vmcnt(6)
	v_mul_f32_e32 v243, v243, v157
	v_mul_f32_e32 v243, v243, v80
	v_lshlrev_b32_e32 v230, 16, v42
	v_mul_f32_e32 v243, v243, v230
	v_mul_f32_e32 v244, v244, v157
	v_mul_f32_e32 v244, v244, v81
	v_and_b32_e32 v230, 0xffff0000, v42
	v_mul_f32_e32 v244, v244, v230
	v_mul_f32_e32 v245, v245, v157
	v_mul_f32_e32 v245, v245, v82
	v_lshlrev_b32_e32 v230, 16, v43
	v_mul_f32_e32 v245, v245, v230
	v_mul_f32_e32 v246, v246, v157
	v_mul_f32_e32 v246, v246, v83
	v_and_b32_e32 v230, 0xffff0000, v43
	v_mul_f32_e32 v246, v246, v230
	v_cvt_pk_bf16_f32 v224, v243, v244
	v_cvt_pk_bf16_f32 v225, v245, v246
	s_waitcnt vmcnt(5)
	v_mul_f32_e32 v159, v159, v157
	v_mul_f32_e32 v159, v159, v84
	v_lshlrev_b32_e32 v230, 16, v44
	v_mul_f32_e32 v159, v159, v230
	v_mul_f32_e32 v155, v155, v157
	v_mul_f32_e32 v155, v155, v85
	v_and_b32_e32 v230, 0xffff0000, v44
	v_mul_f32_e32 v155, v155, v230
	v_mul_f32_e32 v153, v153, v157
	v_mul_f32_e32 v153, v153, v86
	v_lshlrev_b32_e32 v230, 16, v45
	v_mul_f32_e32 v153, v153, v230
	v_mul_f32_e32 v101, v101, v157
	v_mul_f32_e32 v101, v101, v87
	v_and_b32_e32 v230, 0xffff0000, v45
	v_mul_f32_e32 v101, v101, v230
	v_cvt_pk_bf16_f32 v226, v159, v155
	v_cvt_pk_bf16_f32 v227, v153, v101
	s_nop 1
	v_permlane16_swap_b32_e32 v224, v226
	v_permlane16_swap_b32_e32 v225, v227
	global_store_dwordx4 v[130:131], v[224:227], off offset:128
	s_waitcnt vmcnt(5)
	v_mul_f32_e32 v247, v247, v157
	v_mul_f32_e32 v247, v247, v88
	v_lshlrev_b32_e32 v230, 16, v46
	v_mul_f32_e32 v247, v247, v230
	v_mul_f32_e32 v248, v248, v157
	v_mul_f32_e32 v248, v248, v89
	v_and_b32_e32 v230, 0xffff0000, v46
	v_mul_f32_e32 v248, v248, v230
	v_mul_f32_e32 v249, v249, v157
	v_mul_f32_e32 v249, v249, v90
	v_lshlrev_b32_e32 v230, 16, v47
	v_mul_f32_e32 v249, v249, v230
	v_mul_f32_e32 v250, v250, v157
	v_mul_f32_e32 v250, v250, v91
	v_and_b32_e32 v230, 0xffff0000, v47
	v_mul_f32_e32 v250, v250, v230
	v_cvt_pk_bf16_f32 v224, v247, v248
	v_cvt_pk_bf16_f32 v225, v249, v250
	s_waitcnt vmcnt(4)
	v_mul_f32_e32 v251, v251, v157
	v_mul_f32_e32 v251, v251, v92
	v_lshlrev_b32_e32 v230, 16, v48
	v_mul_f32_e32 v251, v251, v230
	v_mul_f32_e32 v252, v252, v157
	v_mul_f32_e32 v252, v252, v93
	v_and_b32_e32 v230, 0xffff0000, v48
	v_mul_f32_e32 v252, v252, v230
	v_mul_f32_e32 v253, v253, v157
	v_mul_f32_e32 v253, v253, v94
	v_lshlrev_b32_e32 v230, 16, v49
	v_mul_f32_e32 v253, v253, v230
	v_mul_f32_e32 v141, v141, v157
	v_mul_f32_e32 v141, v141, v95
	v_and_b32_e32 v230, 0xffff0000, v49
	v_mul_f32_e32 v141, v141, v230
	v_cvt_pk_bf16_f32 v226, v251, v252
	v_cvt_pk_bf16_f32 v227, v253, v141
	s_nop 1
	v_permlane16_swap_b32_e32 v224, v226
	v_permlane16_swap_b32_e32 v225, v227
	global_store_dwordx4 v[130:131], v[224:227], off offset:192
	s_waitcnt vmcnt(4)
; __device__ __forceinline__ unsigned cvt_pk_bf16(float lo, float hi) { unsigned r; asm volatile("v_cvt_pk_bf16_f32 %0, %1, %2" : "=v"(r) : "v"(lo), "v"(hi)); return r; }
; __device__ __forceinline__ float bflo(unsigned u) { return __uint_as_float(u << 16); }
; __device__ __forceinline__ float bfhi(unsigned u) { return __uint_as_float(u & 0xffff0000u); }
; __device__ __forceinline__ void mout_phase(const Params& p, LAS unsigned char* lds) {
;     ...
;             for (int nb = 0; nb < 16; ++nb) { const int dv = nb * 16 + 4 * fq; const f32x4 gn = *(const f32x4*)(ng + dv); const u32x2 ov = *(const u32x2*)(og + dv);
;                 u32x2 o; o.x = cvt_pk_bf16(acc[nb][0] * rstd * gn[0] * bflo(ov.x), acc[nb][1] * rstd * gn[1] * bfhi(ov.x));
;                 o.y = cvt_pk_bf16(acc[nb][2] * rstd * gn[2] * bflo(ov.y), acc[nb][3] * rstd * gn[3] * bfhi(ov.y));
;                 *(u32x2*)(cat + dv) = o;
;                 if ((nb & 3) == 3) asm volatile("" ::: "memory"); }
	v_mul_f32_e32 v126, v126, v157
	v_mul_f32_e32 v126, v126, v96
	v_lshlrev_b32_e32 v230, 16, v50
	v_mul_f32_e32 v126, v126, v230
	v_mul_f32_e32 v128, v128, v157
	v_mul_f32_e32 v128, v128, v97
	v_and_b32_e32 v230, 0xffff0000, v50
	v_mul_f32_e32 v128, v128, v230
	v_mul_f32_e32 v180, v180, v157
	v_mul_f32_e32 v180, v180, v98
	v_lshlrev_b32_e32 v230, 16, v51
	v_mul_f32_e32 v180, v180, v230
	v_mul_f32_e32 v182, v182, v157
	v_mul_f32_e32 v182, v182, v99
	v_and_b32_e32 v230, 0xffff0000, v51
	v_mul_f32_e32 v182, v182, v230
	v_cvt_pk_bf16_f32 v224, v126, v128
	v_cvt_pk_bf16_f32 v225, v180, v182
	global_load_dwordx4 v[68:71], v[106:107], off offset:576
	global_load_dwordx4 v[72:75], v[106:107], off offset:640
	global_load_dwordx4 v[76:79], v[106:107], off offset:704
	global_load_dwordx4 v[80:83], v[106:107], off offset:768
	global_load_dwordx4 v[84:87], v[106:107], off offset:832
	global_load_dwordx4 v[88:91], v[106:107], off offset:896
	global_load_dwordx4 v[92:95], v[106:107], off offset:960
	s_waitcnt vmcnt(6)
	v_mul_f32_e32 v127, v127, v157
	v_mul_f32_e32 v127, v127, v68
	v_lshlrev_b32_e32 v230, 16, v52
	v_mul_f32_e32 v127, v127, v230
	v_mul_f32_e32 v129, v129, v157
	v_mul_f32_e32 v129, v129, v69
	v_and_b32_e32 v230, 0xffff0000, v52
	v_mul_f32_e32 v129, v129, v230
	v_mul_f32_e32 v181, v181, v157
	v_mul_f32_e32 v181, v181, v70
	v_lshlrev_b32_e32 v230, 16, v53
	v_mul_f32_e32 v181, v181, v230
	v_mul_f32_e32 v183, v183, v157
	v_mul_f32_e32 v183, v183, v71
	v_and_b32_e32 v230, 0xffff0000, v53
	v_mul_f32_e32 v183, v183, v230
	v_cvt_pk_bf16_f32 v226, v127, v129
	v_cvt_pk_bf16_f32 v227, v181, v183
	s_nop 1
	v_permlane16_swap_b32_e32 v224, v226
	v_permlane16_swap_b32_e32 v225, v227
	global_store_dwordx4 v[130:131], v[224:227], off offset:256
	s_waitcnt vmcnt(6)
	v_mul_f32_e32 v118, v118, v157
	v_mul_f32_e32 v118, v118, v72
	v_lshlrev_b32_e32 v230, 16, v54
	v_mul_f32_e32 v118, v118, v230
	v_mul_f32_e32 v120, v120, v157
	v_mul_f32_e32 v120, v120, v73
	v_and_b32_e32 v230, 0xffff0000, v54
	v_mul_f32_e32 v120, v120, v230
	v_mul_f32_e32 v122, v122, v157
	v_mul_f32_e32 v122, v122, v74
	v_lshlrev_b32_e32 v230, 16, v55
	v_mul_f32_e32 v122, v122, v230
	v_mul_f32_e32 v124, v124, v157
	v_mul_f32_e32 v124, v124, v75
	v_and_b32_e32 v230, 0xffff0000, v55
	v_mul_f32_e32 v124, v124, v230
	v_cvt_pk_bf16_f32 v224, v118, v120
	v_cvt_pk_bf16_f32 v225, v122, v124
	s_waitcnt vmcnt(5)
	v_mul_f32_e32 v119, v119, v157
	v_mul_f32_e32 v119, v119, v76
	v_lshlrev_b32_e32 v230, 16, v56
	v_mul_f32_e32 v119, v119, v230
	v_mul_f32_e32 v121, v121, v157
	v_mul_f32_e32 v121, v121, v77
	v_and_b32_e32 v230, 0xffff0000, v56
	v_mul_f32_e32 v121, v121, v230
	v_mul_f32_e32 v123, v123, v157
	v_mul_f32_e32 v123, v123, v78
	v_lshlrev_b32_e32 v230, 16, v57
	v_mul_f32_e32 v123, v123, v230
	v_mul_f32_e32 v125, v125, v157
	v_mul_f32_e32 v125, v125, v79
	v_and_b32_e32 v230, 0xffff0000, v57
	v_mul_f32_e32 v125, v125, v230
	v_cvt_pk_bf16_f32 v226, v119, v121
	v_cvt_pk_bf16_f32 v227, v123, v125
	s_nop 1
	v_permlane16_swap_b32_e32 v224, v226
	v_permlane16_swap_b32_e32 v225, v227
	global_store_dwordx4 v[130:131], v[224:227], off offset:320
	s_waitcnt vmcnt(5)
	v_mul_f32_e32 v104, v104, v157
	v_mul_f32_e32 v104, v104, v80
	v_lshlrev_b32_e32 v230, 16, v58
	v_mul_f32_e32 v104, v104, v230
	v_mul_f32_e32 v132, v132, v157
	v_mul_f32_e32 v132, v132, v81
	v_and_b32_e32 v230, 0xffff0000, v58
	v_mul_f32_e32 v132, v132, v230
	v_mul_f32_e32 v134, v134, v157
	v_mul_f32_e32 v134, v134, v82
	v_lshlrev_b32_e32 v230, 16, v59
	v_mul_f32_e32 v134, v134, v230
	v_mul_f32_e32 v178, v178, v157
	v_mul_f32_e32 v178, v178, v83
	v_and_b32_e32 v230, 0xffff0000, v59
	v_mul_f32_e32 v178, v178, v230
	v_cvt_pk_bf16_f32 v224, v104, v132
	v_cvt_pk_bf16_f32 v225, v134, v178
	s_waitcnt vmcnt(4)
	v_mul_f32_e32 v105, v105, v157
	v_mul_f32_e32 v105, v105, v84
	v_lshlrev_b32_e32 v230, 16, v60
	v_mul_f32_e32 v105, v105, v230
	v_mul_f32_e32 v133, v133, v157
	v_mul_f32_e32 v133, v133, v85
	v_and_b32_e32 v230, 0xffff0000, v60
	v_mul_f32_e32 v133, v133, v230
	v_mul_f32_e32 v135, v135, v157
	v_mul_f32_e32 v135, v135, v86
	v_lshlrev_b32_e32 v230, 16, v61
	v_mul_f32_e32 v135, v135, v230
	v_mul_f32_e32 v179, v179, v157
	v_mul_f32_e32 v179, v179, v87
	v_and_b32_e32 v230, 0xffff0000, v61
	v_mul_f32_e32 v179, v179, v230
	v_cvt_pk_bf16_f32 v226, v105, v133
	v_cvt_pk_bf16_f32 v227, v135, v179
	s_nop 1
	v_permlane16_swap_b32_e32 v224, v226
	v_permlane16_swap_b32_e32 v225, v227
	global_store_dwordx4 v[130:131], v[224:227], off offset:384
	s_waitcnt vmcnt(4)
	v_mul_f32_e32 v110, v110, v157
	v_mul_f32_e32 v110, v110, v88
	v_lshlrev_b32_e32 v230, 16, v62
	v_mul_f32_e32 v110, v110, v230
	v_mul_f32_e32 v112, v112, v157
	v_mul_f32_e32 v112, v112, v89
	v_and_b32_e32 v230, 0xffff0000, v62
	v_mul_f32_e32 v112, v112, v230
	v_mul_f32_e32 v114, v114, v157
	v_mul_f32_e32 v114, v114, v90
	v_lshlrev_b32_e32 v230, 16, v63
	v_mul_f32_e32 v114, v114, v230
	v_mul_f32_e32 v116, v116, v157
	v_mul_f32_e32 v116, v116, v91
	v_and_b32_e32 v230, 0xffff0000, v63
	v_mul_f32_e32 v116, v116, v230
	v_cvt_pk_bf16_f32 v224, v110, v112
	v_cvt_pk_bf16_f32 v225, v114, v116
	s_waitcnt vmcnt(3)
	v_mul_f32_e32 v111, v111, v157
	v_mul_f32_e32 v111, v111, v92
	v_lshlrev_b32_e32 v230, 16, v64
	v_mul_f32_e32 v111, v111, v230
	v_mul_f32_e32 v113, v113, v157
	v_mul_f32_e32 v113, v113, v93
	v_and_b32_e32 v230, 0xffff0000, v64
	v_mul_f32_e32 v113, v113, v230
	v_mul_f32_e32 v115, v115, v157
	v_mul_f32_e32 v115, v115, v94
	v_lshlrev_b32_e32 v230, 16, v65
	v_mul_f32_e32 v115, v115, v230
	v_mul_f32_e32 v117, v117, v157
	v_mul_f32_e32 v117, v117, v95
	v_and_b32_e32 v230, 0xffff0000, v65
	v_mul_f32_e32 v117, v117, v230
	v_cvt_pk_bf16_f32 v226, v111, v113
	v_cvt_pk_bf16_f32 v227, v115, v117
	s_nop 1
	v_permlane16_swap_b32_e32 v224, v226
	v_permlane16_swap_b32_e32 v225, v227
	global_store_dwordx4 v[130:131], v[224:227], off offset:448
	v_mov_b32_e32 v244, v213
